# v46 + XCD-local seams: waiters poll the arrival counter (one L2 round trip less); last arriver acquires before publishing and does not wait for the publish ack in light mode
# baseline (speedup 1.0000x reference)
.LBB0_525:
	s_or_b64 exec, exec, s[8:9]
	v_cvt_f32_u32_e32 v6, v4
	s_waitcnt vmcnt(0)
	v_readfirstlane_b32 s0, v5
	v_sub_u32_e32 v5, 0, v4
	v_rcp_iflag_f32_e32 v6, v6
	v_add_u32_e32 v7, s0, v3
	v_mul_f32_e32 v6, 0x4f7ffffe, v6
	v_cvt_u32_f32_e32 v6, v6
	v_mul_lo_u32 v3, v5, v6
	v_mul_hi_u32 v3, v6, v3
	v_add_u32_e32 v3, v6, v3
	v_mul_hi_u32 v3, v7, v3
	v_mul_lo_u32 v5, v3, v4
	v_sub_u32_e32 v5, v7, v5
	v_add_u32_e32 v6, 1, v3
	v_cmp_ge_u32_e32 vcc, v5, v4
	s_nop 1
	v_cndmask_b32_e32 v3, v3, v6, vcc
	v_sub_u32_e32 v6, v5, v4
	v_cndmask_b32_e32 v5, v5, v6, vcc
	v_add_u32_e32 v6, 1, v3
	v_cmp_ge_u32_e32 vcc, v5, v4
	v_add_u32_e32 v5, 1, v7
	s_nop 0
	v_cndmask_b32_e32 v3, v3, v6, vcc
	v_mul_lo_u32 v6, v4, v3
	v_add_u32_e32 v4, v6, v4
	v_cmp_ne_u32_e32 vcc, v5, v4
	s_and_saveexec_b64 s[0:1], vcc
	s_xor_b64 s[0:1], exec, s[0:1]
	s_cbranch_execz .LBB0_539
	s_waitcnt lgkmcnt(0)
	v_readlane_b32 s99, v244, 42
	buffer_inv sc1
	v_add_u32_e32 v247, 1, v3
	s_movk_i32 s98, 0x2400
	s_cmp_eq_u32 s99, 0
	s_cselect_b32 s98, 0x1400, s98
	s_cselect_b64 vcc, -1, 0
	s_add_u32 s12, s6, s98
	s_addc_u32 s13, s7, 0
	v_cndmask_b32_e32 v247, v247, v4, vcc
	v_mov_b32_e32 v2, 0
	global_load_dword v2, v2, s[12:13] sc1
	s_waitcnt vmcnt(0)
	v_cmp_lt_u32_e32 vcc, v2, v247
	s_and_saveexec_b64 s[8:9], vcc
	s_cbranch_execz .LBB0_538
	s_add_u32 s10, s34, 0x4200
	s_addc_u32 s11, s35, 0
	s_mov_b32 s3, 1
	s_mov_b64 s[14:15], 0
	v_mov_b32_e32 v2, 0
	s_branch .LBB0_529

.LBB0_533:
	global_load_dword v4, v2, s[12:13] sc1
	s_add_i32 s3, s3, 1
	s_mov_b64 s[54:55], -1
	s_waitcnt vmcnt(0)
	v_cmp_ge_u32_e32 vcc, v4, v247
	s_orn2_b64 s[52:53], vcc, exec
	s_branch .LBB0_528

.LBB0_560:
	s_mov_b64 s[0:1], exec
	s_waitcnt lgkmcnt(0)
	v_mbcnt_lo_u32_b32 v2, s0, 0
	v_mbcnt_hi_u32_b32 v2, s1, v2
	v_cmp_eq_u32_e32 vcc, 0, v2
	buffer_inv sc1
	s_waitcnt vmcnt(0)
	s_and_saveexec_b64 s[8:9], vcc
	s_cbranch_execz .LBB0_562
	s_bcnt1_i32_b64 s0, s[0:1]
	v_mov_b32_e32 v2, 0x2000
	v_mov_b32_e32 v3, s0
	global_atomic_add v2, v3, s[6:7] offset:1024
.LBB0_562:
	s_or_b64 exec, exec, s[8:9]
	v_readlane_b32 s99, v244, 42
	s_cmp_eq_u32 s99, 0
	s_cbranch_scc1 .Lhop_1
	s_waitcnt vmcnt(0)
.Lhop_1:
.LBB0_563:
	s_or_b64 exec, exec, s[4:5]
	s_waitcnt lgkmcnt(0)
	s_barrier

.LBB0_631:
	s_or_b64 exec, exec, s[10:11]
	v_cvt_f32_u32_e32 v6, v4
	s_waitcnt vmcnt(0)
	v_readfirstlane_b32 s0, v5
	v_sub_u32_e32 v5, 0, v4
	v_rcp_iflag_f32_e32 v6, v6
	v_add_u32_e32 v7, s0, v3
	v_mul_f32_e32 v6, 0x4f7ffffe, v6
	v_cvt_u32_f32_e32 v6, v6
	v_mul_lo_u32 v3, v5, v6
	v_mul_hi_u32 v3, v6, v3
	v_add_u32_e32 v3, v6, v3
	v_mul_hi_u32 v3, v7, v3
	v_mul_lo_u32 v5, v3, v4
	v_sub_u32_e32 v5, v7, v5
	v_add_u32_e32 v6, 1, v3
	v_cmp_ge_u32_e32 vcc, v5, v4
	s_nop 1
	v_cndmask_b32_e32 v3, v3, v6, vcc
	v_sub_u32_e32 v6, v5, v4
	v_cndmask_b32_e32 v5, v5, v6, vcc
	v_add_u32_e32 v6, 1, v3
	v_cmp_ge_u32_e32 vcc, v5, v4
	v_add_u32_e32 v5, 1, v7
	s_nop 0
	v_cndmask_b32_e32 v3, v3, v6, vcc
	v_mul_lo_u32 v6, v4, v3
	v_add_u32_e32 v4, v6, v4
	v_cmp_ne_u32_e32 vcc, v5, v4
	s_and_saveexec_b64 s[0:1], vcc
	s_xor_b64 s[0:1], exec, s[0:1]
	s_cbranch_execz .LBB0_645
	s_waitcnt lgkmcnt(0)
	v_readlane_b32 s99, v244, 42
	buffer_inv sc1
	v_add_u32_e32 v247, 1, v3
	s_movk_i32 s98, 0x2400
	s_cmp_eq_u32 s99, 0
	s_cselect_b32 s98, 0x1400, s98
	s_cselect_b64 vcc, -1, 0
	s_add_u32 s14, s8, s98
	s_addc_u32 s15, s9, 0
	v_cndmask_b32_e32 v247, v247, v4, vcc
	v_mov_b32_e32 v2, 0
	global_load_dword v2, v2, s[14:15] sc1
	s_waitcnt vmcnt(0)
	v_cmp_lt_u32_e32 vcc, v2, v247
	s_and_saveexec_b64 s[10:11], vcc
	s_cbranch_execz .LBB0_644
	s_add_u32 s12, s34, 0x4200
	s_addc_u32 s13, s35, 0
	s_mov_b32 s3, 1
	s_mov_b64 s[40:41], 0
	v_mov_b32_e32 v2, 0
	s_branch .LBB0_635

.LBB0_639:
	global_load_dword v4, v2, s[14:15] sc1
	s_add_i32 s3, s3, 1
	s_mov_b64 s[56:57], -1
	s_waitcnt vmcnt(0)
	v_cmp_ge_u32_e32 vcc, v4, v247
	s_orn2_b64 s[54:55], vcc, exec
	s_branch .LBB0_634

.LBB0_666:
	s_mov_b64 s[0:1], exec
	s_waitcnt lgkmcnt(0)
	v_mbcnt_lo_u32_b32 v2, s0, 0
	v_mbcnt_hi_u32_b32 v2, s1, v2
	v_cmp_eq_u32_e32 vcc, 0, v2
	buffer_inv sc1
	s_waitcnt vmcnt(0)
	s_and_saveexec_b64 s[10:11], vcc
	s_cbranch_execz .LBB0_668
	s_bcnt1_i32_b64 s0, s[0:1]
	v_mov_b32_e32 v2, 0x2000
	v_mov_b32_e32 v3, s0
	global_atomic_add v2, v3, s[8:9] offset:1024
.LBB0_668:
	s_or_b64 exec, exec, s[10:11]
	v_readlane_b32 s99, v244, 42
	s_cmp_eq_u32 s99, 0
	s_cbranch_scc1 .Lhop_2
	s_waitcnt vmcnt(0)
.Lhop_2:
.LBB0_669:
	s_or_b64 exec, exec, s[6:7]
	s_waitcnt lgkmcnt(0)
	s_barrier

.LBB0_1258:
	s_or_b64 exec, exec, s[8:9]
	v_cvt_f32_u32_e32 v5, v3
	s_waitcnt vmcnt(0)
	v_readfirstlane_b32 s0, v4
	v_sub_u32_e32 v4, 0, v3
	v_rcp_iflag_f32_e32 v5, v5
	v_add_u32_e32 v6, s0, v2
	v_mul_f32_e32 v5, 0x4f7ffffe, v5
	v_cvt_u32_f32_e32 v5, v5
	v_mul_lo_u32 v2, v4, v5
	v_mul_hi_u32 v2, v5, v2
	v_add_u32_e32 v2, v5, v2
	v_mul_hi_u32 v2, v6, v2
	v_mul_lo_u32 v4, v2, v3
	v_sub_u32_e32 v4, v6, v4
	v_add_u32_e32 v5, 1, v2
	v_cmp_ge_u32_e32 vcc, v4, v3
	s_nop 1
	v_cndmask_b32_e32 v2, v2, v5, vcc
	v_sub_u32_e32 v5, v4, v3
	v_cndmask_b32_e32 v4, v4, v5, vcc
	v_add_u32_e32 v5, 1, v2
	v_cmp_ge_u32_e32 vcc, v4, v3
	v_add_u32_e32 v4, 1, v6
	s_nop 0
	v_cndmask_b32_e32 v2, v2, v5, vcc
	v_mul_lo_u32 v5, v3, v2
	v_add_u32_e32 v3, v5, v3
	v_cmp_ne_u32_e32 vcc, v4, v3
	s_and_saveexec_b64 s[0:1], vcc
	s_xor_b64 s[0:1], exec, s[0:1]
	s_cbranch_execz .LBB0_1272
	s_waitcnt lgkmcnt(0)
	v_readlane_b32 s99, v244, 42
	buffer_inv sc1
	v_add_u32_e32 v247, 1, v2
	s_movk_i32 s98, 0x2400
	s_cmp_eq_u32 s99, 0
	s_cselect_b32 s98, 0x1400, s98
	s_cselect_b64 vcc, -1, 0
	s_add_u32 s12, s6, s98
	s_addc_u32 s13, s7, 0
	v_cndmask_b32_e32 v247, v247, v3, vcc
	v_mov_b32_e32 v1, 0
	global_load_dword v1, v1, s[12:13] sc1
	s_waitcnt vmcnt(0)
	v_cmp_lt_u32_e32 vcc, v1, v247
	s_and_saveexec_b64 s[8:9], vcc
	s_cbranch_execz .LBB0_1271
	s_add_u32 s10, s34, 0x4200
	s_addc_u32 s11, s35, 0
	s_mov_b32 s3, 1
	s_mov_b64 s[14:15], 0
	v_mov_b32_e32 v1, 0
	s_branch .LBB0_1262

.LBB0_1266:
	global_load_dword v3, v1, s[12:13] sc1
	s_add_i32 s3, s3, 1
	s_mov_b64 s[22:23], -1
	s_waitcnt vmcnt(0)
	v_cmp_ge_u32_e32 vcc, v3, v247
	s_orn2_b64 s[20:21], vcc, exec
	s_branch .LBB0_1261

.LBB0_1293:
	s_mov_b64 s[0:1], exec
	s_waitcnt lgkmcnt(0)
	v_mbcnt_lo_u32_b32 v1, s0, 0
	v_mbcnt_hi_u32_b32 v1, s1, v1
	v_cmp_eq_u32_e32 vcc, 0, v1
	buffer_inv sc1
	s_waitcnt vmcnt(0)
	s_and_saveexec_b64 s[8:9], vcc
	s_cbranch_execz .LBB0_1295
	s_bcnt1_i32_b64 s0, s[0:1]
	v_mov_b32_e32 v1, 0x2000
	v_mov_b32_e32 v2, s0
	global_atomic_add v1, v2, s[6:7] offset:1024

.LBB0_1428:
	s_or_b64 exec, exec, s[8:9]
	v_cvt_f32_u32_e32 v5, v3
	s_waitcnt vmcnt(0)
	v_readfirstlane_b32 s0, v4
	v_sub_u32_e32 v4, 0, v3
	v_rcp_iflag_f32_e32 v5, v5
	v_add_u32_e32 v6, s0, v2
	v_mul_f32_e32 v5, 0x4f7ffffe, v5
	v_cvt_u32_f32_e32 v5, v5
	v_mul_lo_u32 v2, v4, v5
	v_mul_hi_u32 v2, v5, v2
	v_add_u32_e32 v2, v5, v2
	v_mul_hi_u32 v2, v6, v2
	v_mul_lo_u32 v4, v2, v3
	v_sub_u32_e32 v4, v6, v4
	v_add_u32_e32 v5, 1, v2
	v_cmp_ge_u32_e32 vcc, v4, v3
	s_nop 1
	v_cndmask_b32_e32 v2, v2, v5, vcc
	v_sub_u32_e32 v5, v4, v3
	v_cndmask_b32_e32 v4, v4, v5, vcc
	v_add_u32_e32 v5, 1, v2
	v_cmp_ge_u32_e32 vcc, v4, v3
	v_add_u32_e32 v4, 1, v6
	s_nop 0
	v_cndmask_b32_e32 v2, v2, v5, vcc
	v_mul_lo_u32 v5, v3, v2
	v_add_u32_e32 v3, v5, v3
	v_cmp_ne_u32_e32 vcc, v4, v3
	s_and_saveexec_b64 s[0:1], vcc
	s_xor_b64 s[0:1], exec, s[0:1]
	s_cbranch_execz .LBB0_1442
	s_waitcnt lgkmcnt(0)
	v_readlane_b32 s99, v244, 42
	buffer_inv sc1
	v_add_u32_e32 v247, 1, v2
	s_movk_i32 s98, 0x2400
	s_cmp_eq_u32 s99, 0
	s_cselect_b32 s98, 0x1400, s98
	s_cselect_b64 vcc, -1, 0
	s_add_u32 s14, s6, s98
	s_addc_u32 s15, s7, 0
	v_cndmask_b32_e32 v247, v247, v3, vcc
	v_mov_b32_e32 v1, 0
	global_load_dword v1, v1, s[14:15] sc1
	s_waitcnt vmcnt(0)
	v_cmp_lt_u32_e32 vcc, v1, v247
	s_and_saveexec_b64 s[8:9], vcc
	s_cbranch_execz .LBB0_1441
	v_readlane_b32 s12, v244, 58
	v_readlane_b32 s13, v244, 59
	s_add_u32 s12, s12, 0x4200
	s_addc_u32 s13, s13, 0
	s_mov_b32 s38, 1
	s_mov_b64 s[18:19], 0
	v_mov_b32_e32 v1, 0
	s_branch .LBB0_1432

.LBB0_1436:
	global_load_dword v3, v1, s[14:15] sc1
	s_add_i32 s38, s38, 1
	s_mov_b64 s[26:27], -1
	s_waitcnt vmcnt(0)
	v_cmp_ge_u32_e32 vcc, v3, v247
	s_orn2_b64 s[24:25], vcc, exec
	s_branch .LBB0_1431

.LBB0_1574:
	s_or_b64 exec, exec, s[8:9]
	v_cvt_f32_u32_e32 v4, v2
	s_waitcnt vmcnt(0)
	v_readfirstlane_b32 s6, v3
	v_sub_u32_e32 v3, 0, v2
	v_rcp_iflag_f32_e32 v4, v4
	v_add_u32_e32 v5, s6, v1
	v_mul_f32_e32 v4, 0x4f7ffffe, v4
	v_cvt_u32_f32_e32 v4, v4
	v_mul_lo_u32 v1, v3, v4
	v_mul_hi_u32 v1, v4, v1
	v_add_u32_e32 v1, v4, v1
	v_mul_hi_u32 v1, v5, v1
	v_mul_lo_u32 v3, v1, v2
	v_sub_u32_e32 v3, v5, v3
	v_add_u32_e32 v4, 1, v1
	v_cmp_ge_u32_e32 vcc, v3, v2
	s_nop 1
	v_cndmask_b32_e32 v1, v1, v4, vcc
	v_sub_u32_e32 v4, v3, v2
	v_cndmask_b32_e32 v3, v3, v4, vcc
	v_add_u32_e32 v4, 1, v1
	v_cmp_ge_u32_e32 vcc, v3, v2
	v_add_u32_e32 v3, 1, v5
	s_nop 0
	v_cndmask_b32_e32 v1, v1, v4, vcc
	v_mul_lo_u32 v4, v2, v1
	v_add_u32_e32 v2, v4, v2
	v_cmp_ne_u32_e32 vcc, v3, v2
	s_and_saveexec_b64 s[6:7], vcc
	s_xor_b64 s[6:7], exec, s[6:7]
	s_cbranch_execz .LBB0_1588
	v_readlane_b32 s99, v244, 42
	buffer_inv sc1
	v_add_u32_e32 v247, 1, v1
	s_movk_i32 s98, 0x2400
	s_cmp_eq_u32 s99, 0
	s_cselect_b32 s98, 0x1400, s98
	s_cselect_b64 vcc, -1, 0
	s_add_u32 s12, s4, s98
	s_addc_u32 s13, s5, 0
	v_cndmask_b32_e32 v247, v247, v2, vcc
	v_mov_b32_e32 v2, 0
	global_load_dword v2, v2, s[12:13] sc1
	s_waitcnt vmcnt(0)
	v_cmp_lt_u32_e32 vcc, v2, v247
	s_and_saveexec_b64 s[8:9], vcc
	s_cbranch_execz .LBB0_1587
	s_add_u32 s10, s30, 0x4200
	s_addc_u32 s11, s31, 0
	s_mov_b32 s24, 1
	s_mov_b64 s[14:15], 0
	v_mov_b32_e32 v2, 0
	s_branch .LBB0_1578

.LBB0_1582:
	global_load_dword v3, v2, s[12:13] sc1
	s_add_i32 s24, s24, 1
	s_mov_b64 s[20:21], -1
	s_waitcnt vmcnt(0)
	v_cmp_ge_u32_e32 vcc, v3, v247
	s_orn2_b64 s[18:19], vcc, exec
	s_branch .LBB0_1577

.LBB0_1588:
	s_andn2_saveexec_b64 s[6:7], s[6:7]
	s_cbranch_execz .LBB0_1592
	s_mov_b64 s[6:7], exec
	buffer_inv sc1
	s_waitcnt vmcnt(0)
	v_mbcnt_lo_u32_b32 v1, s6, 0
	v_mbcnt_hi_u32_b32 v1, s7, v1
	v_cmp_eq_u32_e32 vcc, 0, v1
	s_and_saveexec_b64 s[8:9], vcc
	s_cbranch_execz .LBB0_1591
	s_bcnt1_i32_b64 s6, s[6:7]
	v_mov_b32_e32 v1, 0x2000
	v_mov_b32_e32 v2, s6
	global_atomic_add v1, v2, s[4:5] offset:1024

.Lhop_5:
.LBB0_1592:
	s_or_b64 exec, exec, s[0:1]
	s_barrier
	s_mov_b64 s[0:1], exec
	v_readlane_b32 s4, v244, 5
	v_readlane_b32 s5, v244, 6
	s_and_b64 s[4:5], s[0:1], s[4:5]
	s_mov_b64 exec, s[4:5]
	s_cbranch_execz .LBB0_1606
	v_mov_b32_e32 v1, 0x4000
	global_load_dword v1, v1, s[30:31] offset:260 sc1
	s_add_u32 s6, s30, 0x4104
	s_addc_u32 s7, s31, 0
	s_waitcnt vmcnt(0)
	v_cmp_le_u32_e32 vcc, s33, v1
	s_cbranch_vccnz .LBB0_1605
	s_add_u32 s4, s30, 0x4200
	s_addc_u32 s5, s31, 0
	s_mov_b32 s14, 1
	v_mov_b32_e32 v1, 0
	s_branch .LBB0_1596

.LBB0_1670:
	s_or_b64 exec, exec, s[10:11]
	v_cvt_f32_u32_e32 v5, v3
	s_waitcnt vmcnt(0)
	v_readfirstlane_b32 s0, v4
	v_sub_u32_e32 v4, 0, v3
	v_rcp_iflag_f32_e32 v5, v5
	v_add_u32_e32 v6, s0, v2
	v_mul_f32_e32 v5, 0x4f7ffffe, v5
	v_cvt_u32_f32_e32 v5, v5
	v_mul_lo_u32 v2, v4, v5
	v_mul_hi_u32 v2, v5, v2
	v_add_u32_e32 v2, v5, v2
	v_mul_hi_u32 v2, v6, v2
	v_mul_lo_u32 v4, v2, v3
	v_sub_u32_e32 v4, v6, v4
	v_add_u32_e32 v5, 1, v2
	v_cmp_ge_u32_e32 vcc, v4, v3
	s_nop 1
	v_cndmask_b32_e32 v2, v2, v5, vcc
	v_sub_u32_e32 v5, v4, v3
	v_cndmask_b32_e32 v4, v4, v5, vcc
	v_add_u32_e32 v5, 1, v2
	v_cmp_ge_u32_e32 vcc, v4, v3
	v_add_u32_e32 v4, 1, v6
	s_nop 0
	v_cndmask_b32_e32 v2, v2, v5, vcc
	v_mul_lo_u32 v5, v3, v2
	v_add_u32_e32 v3, v5, v3
	v_cmp_ne_u32_e32 vcc, v4, v3
	s_and_saveexec_b64 s[0:1], vcc
	s_xor_b64 s[0:1], exec, s[0:1]
	s_cbranch_execz .LBB0_1684
	s_waitcnt lgkmcnt(0)
	v_readlane_b32 s99, v244, 42
	buffer_inv sc1
	v_add_u32_e32 v247, 1, v2
	s_movk_i32 s98, 0x2400
	s_cmp_eq_u32 s99, 0
	s_cselect_b32 s98, 0x1400, s98
	s_cselect_b64 vcc, -1, 0
	s_add_u32 s14, s8, s98
	s_addc_u32 s15, s9, 0
	v_cndmask_b32_e32 v247, v247, v3, vcc
	v_mov_b32_e32 v1, 0
	global_load_dword v1, v1, s[14:15] sc1
	s_waitcnt vmcnt(0)
	v_cmp_lt_u32_e32 vcc, v1, v247
	s_and_saveexec_b64 s[10:11], vcc
	s_cbranch_execz .LBB0_1683
	s_add_u32 s12, s34, 0x4200
	s_addc_u32 s13, s35, 0
	s_mov_b32 s3, 1
	s_mov_b64 s[16:17], 0
	v_mov_b32_e32 v1, 0
	s_branch .LBB0_1674

.LBB0_1678:
	global_load_dword v3, v1, s[14:15] sc1
	s_add_i32 s3, s3, 1
	s_mov_b64 s[22:23], -1
	s_waitcnt vmcnt(0)
	v_cmp_ge_u32_e32 vcc, v3, v247
	s_orn2_b64 s[20:21], vcc, exec
	s_branch .LBB0_1673

.LBB0_1705:
	s_mov_b64 s[0:1], exec
	s_waitcnt lgkmcnt(0)
	v_mbcnt_lo_u32_b32 v1, s0, 0
	v_mbcnt_hi_u32_b32 v1, s1, v1
	v_cmp_eq_u32_e32 vcc, 0, v1
	buffer_inv sc1
	s_waitcnt vmcnt(0)
	s_and_saveexec_b64 s[10:11], vcc
	s_cbranch_execz .LBB0_1707
	s_bcnt1_i32_b64 s0, s[0:1]
	v_mov_b32_e32 v1, 0x2000
	v_mov_b32_e32 v2, s0
	global_atomic_add v1, v2, s[8:9] offset:1024

.LBB0_1758:
	global_load_dword v3, v1, s[12:13] sc1
	s_add_i32 s3, s3, 1
	s_mov_b64 s[20:21], -1
	s_waitcnt vmcnt(0)
	v_cmp_ge_u32_e32 vcc, v3, v247
	s_orn2_b64 s[18:19], vcc, exec
	s_branch .LBB0_1753

.Lhop_7:
.LBB0_1788:
	s_or_b64 exec, exec, s[4:5]
	v_readlane_b32 s0, v244, 40
	v_readlane_b32 s1, v244, 41
	s_andn2_b64 vcc, exec, s[0:1]
	s_waitcnt lgkmcnt(0)
	s_barrier
	s_cbranch_vccnz .LBB0_1803
	s_mov_b64 s[0:1], exec
	v_readlane_b32 s4, v244, 5
	v_readlane_b32 s5, v244, 6
	s_and_b64 s[4:5], s[0:1], s[4:5]
	s_mov_b64 exec, s[4:5]
	s_cbranch_execz .LBB0_1802
	v_mov_b32_e32 v1, 0x4000
	global_load_dword v1, v1, s[34:35] offset:272 sc1
	s_add_u32 s6, s34, 0x4110
	s_addc_u32 s7, s35, 0
	s_waitcnt vmcnt(0)
	v_cmp_le_u32_e32 vcc, s33, v1
	s_cbranch_vccnz .LBB0_1802
	s_add_u32 s4, s34, 0x4200
	s_addc_u32 s5, s35, 0
	s_mov_b32 s3, 1
	v_mov_b32_e32 v1, 0
	s_branch .LBB0_1793
